# adds: running max folded into MFMA accumulator init in selected FAST path, batched importance key loads, wide LDS zero-fill
# speedup vs baseline: 1.0428x; 1.0032x over previous
.LBB0_700:
	s_lshr_b32 s0, s42, 5
	s_xor_b32 s0, s0, s42
	s_lshr_b32 s2, s42, 1
	s_and_b32 s45, s0, 1
	s_cmp_lt_u32 s42, 64
	v_readlane_b32 s0, v252, 61
	v_readlane_b32 s1, v252, 62
	s_cselect_b32 s46, s1, s0
	s_or_b32 s0, s46, 31
	s_bfe_u32 s1, s42, 0x50001
	v_mov_b32_e32 v67, v194
	s_sub_i32 s39, s0, s1
	s_lshl_b32 s47, s39, 5
	v_readfirstlane_b32 s0, v67
	s_ashr_i32 s80, s0, 6
	s_lshl_b32 s43, s80, 2
	v_readlane_b32 s48, v251, 54
	s_add_i32 s44, s43, s47
	v_bfe_u32 v120, v67, 2, 2
	s_waitcnt vmcnt(5)
	v_and_b32_e32 v52, 3, v67
	v_readlane_b32 s54, v251, 60
	v_readlane_b32 s55, v251, 61
	v_or_b32_e32 v103, s44, v120
	v_lshl_or_b32 v22, s45, 2, v52
	v_mov_b64_e32 v[2:3], s[54:55]
	v_mad_i64_i32 v[2:3], s[0:1], v103, s3, v[2:3]
	v_lshlrev_b32_e32 v0, 7, v22
	v_mul_u32_u24_e32 v12, 3, v22
	v_lshl_add_u64 v[4:5], v[2:3], 0, v[0:1]
	s_mov_b64 s[0:1], 0x1400
	v_lshlrev_b32_e32 v12, 1, v12
	v_mov_b32_e32 v13, v1
	v_lshl_add_u64 v[92:93], v[4:5], 0, s[0:1]
	v_lshl_add_u64 v[2:3], v[2:3], 0, v[12:13]
	s_mov_b64 s[0:1], 0x1e00
	v_and_b32_e32 v0, 48, v67
	v_lshl_add_u64 v[12:13], v[2:3], 0, s[0:1]
	v_add_co_u32_e32 v2, vcc, 0x1000, v2
	v_lshl_add_u64 v[8:9], v[92:93], 0, v[0:1]
	s_nop 0
	v_addc_co_u32_e32 v3, vcc, 0, v3, vcc
	global_load_dwordx4 v[4:7], v[8:9], off
	s_nop 0
	global_load_dwordx4 v[8:11], v[8:9], off offset:64
	s_nop 0
	global_load_dword v94, v[2:3], off offset:3584
	global_load_ushort v95, v[12:13], off offset:4
	v_and_b32_e32 v86, 63, v67
	v_bfe_u32 v21, v67, 4, 2
	s_mul_i32 s81, s80, 0x2100
	v_and_b32_e32 v54, 15, v67
	v_lshlrev_b32_e32 v53, 3, v21
	v_mov_b32_e32 v244, 0
	v_mov_b32_e32 v245, 0
	v_mov_b32_e32 v246, 0
	v_mov_b32_e32 v247, 0
	v_lshl_add_u32 v2, v86, 4, s81
	v_lshl_add_u32 v3, v54, 2, s81
	v_readlane_b32 s49, v251, 55
	v_readlane_b32 s50, v251, 56
	v_readlane_b32 s51, v251, 57
	v_readlane_b32 s52, v251, 58
	v_readlane_b32 s53, v251, 59
	v_readlane_b32 s56, v251, 62
	v_readlane_b32 s57, v251, 63
	v_readlane_b32 s58, v252, 0
	v_readlane_b32 s59, v252, 1
	v_readlane_b32 s60, v252, 2
	v_readlane_b32 s61, v252, 3
	v_readlane_b32 s62, v252, 4
	v_readlane_b32 s63, v252, 5
	ds_write_b128 v2, v[244:247]
	ds_write_b128 v2, v[244:247] offset:1024
	ds_write_b128 v2, v[244:247] offset:2048
	ds_write_b128 v2, v[244:247] offset:3072
	ds_write_b128 v2, v[244:247] offset:4096
	ds_write_b128 v2, v[244:247] offset:5120
	ds_write_b128 v2, v[244:247] offset:6144
	ds_write_b128 v2, v[244:247] offset:7168
	ds_write_b32 v3, v1 offset:8192
	s_lshl_b32 s0, s39, 1
	s_add_i32 s0, s0, 64
	v_readlane_b32 s48, v251, 54
	v_lshlrev_b32_e32 v3, 3, v67
	v_ashrrev_i32_e32 v2, 3, v67
	s_lshr_b32 s12, s0, 6
	s_lshl_b32 s88, s45, 17
	v_readlane_b32 s60, v252, 2
	v_and_b32_e32 v20, 56, v3
	v_readlane_b32 s61, v252, 3
	s_add_u32 s0, s60, s88
	v_ashrrev_i32_e32 v3, 31, v2
	s_addc_u32 s1, s61, 0
	v_lshlrev_b64 v[44:45], 7, v[2:3]
	v_lshl_add_u64 v[12:13], s[0:1], 0, v[44:45]
	v_lshlrev_b32_e32 v80, 1, v20
	v_mov_b32_e32 v81, v1
	s_add_i32 s0, s12, -1
	s_mov_b32 s1, s89
	v_lshl_add_u64 v[36:37], v[12:13], 0, v[80:81]
	s_lshl_b64 s[0:1], s[0:1], 13
	v_lshl_add_u64 v[12:13], v[36:37], 0, s[0:1]
	global_load_dwordx4 v[12:15], v[12:13], off
	s_cmp_gt_u32 s39, 31
	s_cselect_b64 s[0:1], -1, 0
	s_cmp_lt_u32 s39, 32
	v_readlane_b32 s49, v251, 55
	v_readlane_b32 s50, v251, 56
	v_readlane_b32 s51, v251, 57
	v_readlane_b32 s52, v251, 58
	v_readlane_b32 s53, v251, 59
	v_readlane_b32 s54, v251, 60
	v_readlane_b32 s55, v251, 61
	v_readlane_b32 s56, v251, 62
	v_readlane_b32 s57, v251, 63
	v_readlane_b32 s58, v252, 0
	v_readlane_b32 s59, v252, 1
	v_readlane_b32 s62, v252, 4
	v_readlane_b32 s63, v252, 5
	s_cbranch_scc1 .LBB0_704
	s_lshl_b32 s4, s12, 13
	s_mov_b32 s5, s89
	v_lshl_add_u64 v[16:17], v[36:37], 0, s[4:5]
	v_add_co_u32_e32 v16, vcc, 0xffffc000, v16
	s_nop 1
	v_addc_co_u32_e32 v17, vcc, -1, v17, vcc
	global_load_dwordx4 v[16:19], v[16:17], off
	s_branch .LBB0_705

.LBB0_781:
	s_waitcnt lgkmcnt(0)
	s_lshr_b32 s51, s39, 1
	s_cmp_gt_u32 s39, 31
	s_mov_b64 s[0:1], -1
	s_cbranch_scc0 .LBB0_945
	s_add_i32 s2, s51, -2
	v_cmp_ne_u32_e32 vcc, 0, v86
	v_cmp_ge_i32_e64 s[0:1], s2, v86
	s_waitcnt vmcnt(0)
	v_cmp_eq_u32_e64 s[10:11], 0, v86
	s_and_b64 s[0:1], vcc, s[0:1]
	v_or_b32_e32 v3, 64, v86
	v_cmp_ge_i32_e64 s[8:9], s2, v3
	v_or_b32_e32 v3, 0x80, v86
	v_cmp_ge_i32_e64 s[12:13], s2, v3
	v_or_b32_e32 v3, 0xc0, v86
	v_cmp_ge_i32_e64 s[14:15], s2, v3
	v_lshl_add_u32 v3, v86, 2, s81
	v_add_u32_e32 v192, 0x410, v3
	v_add_u32_e32 v193, 0x820, v3
	v_add_u32_e32 v230, 0xc30, v3
	ds_read2st64_b32 v[160:161], v3 offset0:0 offset1:1
	ds_read2st64_b32 v[162:163], v3 offset0:2 offset1:3
	ds_read2st64_b32 v[164:165], v3 offset0:16 offset1:17
	ds_read2st64_b32 v[166:167], v3 offset0:18 offset1:19
	ds_read2st64_b32 v[168:169], v3 offset0:4 offset1:5
	ds_read2st64_b32 v[170:171], v3 offset0:6 offset1:7
	ds_read2st64_b32 v[172:173], v192 offset0:16 offset1:17
	ds_read2st64_b32 v[174:175], v192 offset0:18 offset1:19
	ds_read2st64_b32 v[176:177], v3 offset0:8 offset1:9
	ds_read2st64_b32 v[178:179], v3 offset0:10 offset1:11
	ds_read2st64_b32 v[180:181], v193 offset0:16 offset1:17
	ds_read2st64_b32 v[182:183], v193 offset0:18 offset1:19
	s_waitcnt lgkmcnt(8)
	ds_read2st64_b32 v[184:185], v3 offset0:12 offset1:13
	ds_read2st64_b32 v[186:187], v3 offset0:14 offset1:15
	ds_read2st64_b32 v[188:189], v230 offset0:16 offset1:17
	ds_read2st64_b32 v[190:191], v230 offset0:18 offset1:19
	v_add_f32_e32 v160, v160, v164
	v_add_u32_e32 v160, 1, v160
	v_add_f32_e32 v161, v161, v165
	v_add_u32_e32 v161, 1, v161
	v_add_f32_e32 v162, v162, v166
	v_add_u32_e32 v162, 1, v162
	v_add_f32_e32 v163, v163, v167
	v_add_u32_e32 v163, 1, v163
	v_cndmask_b32_e64 v42, 0, v160, s[0:1]
	v_cndmask_b32_e64 v40, 0, v161, s[8:9]
	v_cndmask_b32_e64 v41, 0, v162, s[12:13]
	v_cndmask_b32_e64 v35, 0, v163, s[14:15]
	s_waitcnt lgkmcnt(8)
	v_add_f32_e32 v168, v168, v172
	v_add_u32_e32 v168, 1, v168
	v_add_f32_e32 v169, v169, v173
	v_add_u32_e32 v169, 1, v169
	v_add_f32_e32 v170, v170, v174
	v_add_u32_e32 v170, 1, v170
	v_add_f32_e32 v171, v171, v175
	v_add_u32_e32 v171, 1, v171
	v_cndmask_b32_e64 v39, 0, v168, s[0:1]
	v_cndmask_b32_e64 v37, 0, v169, s[8:9]
	v_cndmask_b32_e64 v38, 0, v170, s[12:13]
	v_cndmask_b32_e64 v36, 0, v171, s[14:15]
	s_waitcnt lgkmcnt(4)
	v_add_f32_e32 v176, v176, v180
	v_add_u32_e32 v176, 1, v176
	v_add_f32_e32 v177, v177, v181
	v_add_u32_e32 v177, 1, v177
	v_add_f32_e32 v178, v178, v182
	v_add_u32_e32 v178, 1, v178
	v_add_f32_e32 v179, v179, v183
	v_add_u32_e32 v179, 1, v179
	v_cndmask_b32_e64 v34, 0, v176, s[0:1]
	v_cndmask_b32_e64 v32, 0, v177, s[8:9]
	v_cndmask_b32_e64 v33, 0, v178, s[12:13]
	v_cndmask_b32_e64 v31, 0, v179, s[14:15]
	s_waitcnt lgkmcnt(0)
	v_add_f32_e32 v184, v184, v188
	v_add_u32_e32 v184, 1, v184
	v_add_f32_e32 v185, v185, v189
	v_add_u32_e32 v185, 1, v185
	v_add_f32_e32 v186, v186, v190
	v_add_u32_e32 v186, 1, v186
	v_add_f32_e32 v187, v187, v191
	v_add_u32_e32 v187, 1, v187
	v_cndmask_b32_e64 v30, 0, v184, s[0:1]
	v_cndmask_b32_e64 v28, 0, v185, s[8:9]
	v_cndmask_b32_e64 v29, 0, v186, s[12:13]
	v_cndmask_b32_e64 v3, 0, v187, s[14:15]
.LBB0_814:
	s_mov_b32 s4, 30
	s_mov_b32 s41, 0
	s_mov_b32 s40, 0
	s_mov_b32 s38, 0
	s_mov_b32 s2, 0
	s_mov_b32 s74, 0
	s_mov_b32 s85, 0
	s_mov_b32 s88, 0
	s_mov_b32 s98, 0

.LBB0_977:
	s_and_b64 vcc, exec, s[4:5]
	s_cbranch_vccz .LBB0_981
	s_nop 5
	ds_read_b128 v[160:163], v118
	ds_read_b128 v[164:167], v118 offset:64
	ds_read_b128 v[168:171], v118 offset:2304
	ds_read_b128 v[172:175], v118 offset:2368
	ds_read_b128 v[176:179], v118 offset:4608
	ds_read_b128 v[180:183], v118 offset:4672
	ds_read_b128 v[184:187], v118 offset:6912
	ds_read_b128 v[188:191], v118 offset:6976
	v_or_b32_e32 v60, v98, v108
	v_sub_u32_e32 v60, v103, v60
	v_cvt_f32_i32_e32 v60, v60
	s_mov_b32 s4, 2.0
	s_mov_b32 s5, 0x40400000
	v_fma_f32 v60, -v96, v60, -v106
	v_cndmask_b32_e64 v68, v249, v60, s[8:9]
	v_pk_fma_f32 v[62:63], v[96:97], s[4:5], v[68:69] op_sel_hi:[1,1,0]
	s_mov_b32 s4, 0x41800000
	s_mov_b32 s5, 0x41880000
	v_fma_f32 v60, 0, v96, v68
	v_add_f32_e32 v61, v96, v68
	v_pk_fma_f32 v[66:67], v[90:91], s[90:91], v[68:69] op_sel_hi:[1,1,0]
	v_pk_fma_f32 v[64:65], v[88:89], s[4:5], v[68:69] op_sel_hi:[1,1,0]
	v_pk_fma_f32 v[78:79], v[90:91], s[92:93], v[68:69] op_sel_hi:[1,1,0]
	v_pk_fma_f32 v[76:77], v[88:89], s[34:35], v[68:69] op_sel_hi:[1,1,0]
	v_pk_fma_f32 v[110:111], v[90:91], s[22:23], v[68:69] op_sel_hi:[1,1,0]
	v_pk_fma_f32 v[108:109], v[88:89], s[72:73], v[68:69] op_sel_hi:[1,1,0]
	s_waitcnt lgkmcnt(7)
	v_mfma_f32_16x16x32_bf16 v[60:63], v[160:163], v[4:7], v[60:63]
	s_waitcnt lgkmcnt(6)
	v_mfma_f32_16x16x32_bf16 v[72:75], v[164:167], v[8:11], v[60:63]
	ds_read_b128 v[196:199], v243
	ds_read_b128 v[200:203], v243 offset:64
	s_waitcnt lgkmcnt(7)
	v_mfma_f32_16x16x32_bf16 v[60:63], v[168:171], v[4:7], v[64:67]
	s_waitcnt lgkmcnt(6)
	v_mfma_f32_16x16x32_bf16 v[68:71], v[172:175], v[8:11], v[60:63]
	ds_read_b128 v[204:207], v243 offset:2304
	ds_read_b128 v[208:211], v243 offset:2368
	s_waitcnt lgkmcnt(7)
	v_mfma_f32_16x16x32_bf16 v[60:63], v[176:179], v[4:7], v[76:79]
	s_waitcnt lgkmcnt(6)
	v_mfma_f32_16x16x32_bf16 v[60:63], v[180:183], v[8:11], v[60:63]
	ds_read_b128 v[212:215], v243 offset:4608
	ds_read_b128 v[216:219], v243 offset:4672
	s_waitcnt lgkmcnt(7)
	v_mfma_f32_16x16x32_bf16 v[64:67], v[184:187], v[4:7], v[108:111]
	s_waitcnt lgkmcnt(6)
	v_mfma_f32_16x16x32_bf16 v[64:67], v[188:191], v[8:11], v[64:67]
	ds_read_b128 v[220:223], v243 offset:6912
	ds_read_b128 v[224:227], v243 offset:6976
	v_max3_f32 v76, v72, s36, v73
	v_max3_f32 v76, v76, v74, v75
	v_max3_f32 v76, v76, v68, v69
	v_max3_f32 v76, v76, v70, v71
	v_max3_f32 v76, v76, v60, v61
	v_max3_f32 v76, v76, v62, v63
	s_nop 1
	v_max3_f32 v76, v76, v64, v65
	v_max3_f32 v76, v76, v66, v67
	v_cmp_lt_f32_e32 vcc, 0, v76
	s_cbranch_vccz .LBB0_980
	ds_bpermute_b32 v77, v115, v76
	v_max_f32_e32 v76, v76, v76
	s_waitcnt lgkmcnt(0)
	v_max_f32_e32 v77, v77, v77
	v_max_f32_e32 v76, v76, v77
	ds_bpermute_b32 v77, v114, v76
	s_waitcnt lgkmcnt(0)
	v_max3_f32 v77, 0, v76, v77
	v_sub_f32_e32 v76, 0, v77
	v_exp_f32_e32 v76, v76
	v_add_f32_e32 v106, v106, v77
	v_mul_f32_e32 v107, v107, v76
	v_pk_mul_f32 v[42:43], v[42:43], v[76:77] op_sel_hi:[1,0]
	v_pk_mul_f32 v[40:41], v[40:41], v[76:77] op_sel_hi:[1,0]
	v_pk_mul_f32 v[38:39], v[38:39], v[76:77] op_sel_hi:[1,0]
	v_pk_mul_f32 v[36:37], v[36:37], v[76:77] op_sel_hi:[1,0]
	v_pk_mul_f32 v[34:35], v[34:35], v[76:77] op_sel_hi:[1,0]
	v_pk_mul_f32 v[32:33], v[32:33], v[76:77] op_sel_hi:[1,0]
	v_pk_mul_f32 v[30:31], v[30:31], v[76:77] op_sel_hi:[1,0]
	v_pk_mul_f32 v[28:29], v[28:29], v[76:77] op_sel_hi:[1,0]
	v_sub_f32_e32 v72, v72, v77
	v_sub_f32_e32 v73, v73, v77
	v_sub_f32_e32 v74, v74, v77
	v_sub_f32_e32 v75, v75, v77
	v_sub_f32_e32 v68, v68, v77
	v_sub_f32_e32 v69, v69, v77
	v_sub_f32_e32 v70, v70, v77
	v_sub_f32_e32 v71, v71, v77
	v_sub_f32_e32 v60, v60, v77
	v_sub_f32_e32 v61, v61, v77
	v_sub_f32_e32 v62, v62, v77
	v_sub_f32_e32 v63, v63, v77
	v_sub_f32_e32 v64, v64, v77
	v_sub_f32_e32 v65, v65, v77
	v_sub_f32_e32 v66, v66, v77
	v_sub_f32_e32 v67, v67, v77
.LBB0_980:
	v_exp_f32_e32 v72, v72
	v_exp_f32_e32 v73, v73
	v_exp_f32_e32 v74, v74
	v_exp_f32_e32 v75, v75
	v_add_f32_e32 v76, 0, v72
	v_exp_f32_e32 v68, v68
	v_add_f32_e32 v76, v73, v76
	v_exp_f32_e32 v69, v69
	v_add_f32_e32 v76, v74, v76
	v_exp_f32_e32 v70, v70
	v_add_f32_e32 v76, v75, v76
	v_exp_f32_e32 v71, v71
	v_add_f32_e32 v76, v68, v76
	v_exp_f32_e32 v60, v60
	v_add_f32_e32 v76, v69, v76
	v_exp_f32_e32 v61, v61
	v_add_f32_e32 v76, v70, v76
	v_exp_f32_e32 v62, v62
	v_add_f32_e32 v108, v71, v76
	v_exp_f32_e32 v63, v63
	v_cvt_pk_bf16_f32 v78, v68, v69
	v_add_f32_e32 v68, v60, v108
	v_exp_f32_e32 v64, v64
	v_add_f32_e32 v68, v61, v68
	v_exp_f32_e32 v65, v65
	v_add_f32_e32 v68, v62, v68
	v_exp_f32_e32 v66, v66
	v_add_f32_e32 v68, v63, v68
	v_exp_f32_e32 v67, v67
	v_add_f32_e32 v68, v64, v68
	v_add_f32_e32 v68, v65, v68
	v_add_f32_e32 v68, v66, v68
	v_add_f32_e32 v68, v67, v68
	v_cvt_pk_bf16_f32 v60, v60, v61
	v_cvt_pk_bf16_f32 v61, v62, v63
	v_cvt_pk_bf16_f32 v62, v64, v65
	v_cvt_pk_bf16_f32 v63, v66, v67
	v_cvt_pk_bf16_f32 v76, v72, v73
	v_cvt_pk_bf16_f32 v77, v74, v75
	v_cvt_pk_bf16_f32 v79, v70, v71
	v_add_f32_e32 v107, v107, v68
	s_waitcnt lgkmcnt(0)
	v_mfma_f32_16x16x32_bf16 v[40:43], v[196:199], v[76:79], v[40:43]
	v_mfma_f32_16x16x32_bf16 v[36:39], v[204:207], v[76:79], v[36:39]
	v_mfma_f32_16x16x32_bf16 v[32:35], v[212:215], v[76:79], v[32:35]
	v_mfma_f32_16x16x32_bf16 v[28:31], v[220:223], v[76:79], v[28:31]
	v_mfma_f32_16x16x32_bf16 v[40:43], v[200:203], v[60:63], v[40:43]
	v_mfma_f32_16x16x32_bf16 v[36:39], v[208:211], v[60:63], v[36:39]
	v_mfma_f32_16x16x32_bf16 v[32:35], v[216:219], v[60:63], v[32:35]
	v_mfma_f32_16x16x32_bf16 v[28:31], v[224:227], v[60:63], v[28:31]
	s_branch .LBB0_982

.LBB0_992:
	s_and_b64 vcc, exec, s[4:5]
	s_cbranch_vccz .LBB0_996
	s_nop 5
	ds_read_b128 v[160:163], v119
	ds_read_b128 v[164:167], v119 offset:64
	ds_read_b128 v[168:171], v119 offset:2304
	ds_read_b128 v[172:175], v119 offset:2368
	ds_read_b128 v[176:179], v119 offset:4608
	ds_read_b128 v[180:183], v119 offset:4672
	ds_read_b128 v[184:187], v119 offset:6912
	ds_read_b128 v[188:191], v119 offset:6976
	v_or_b32_e32 v60, v98, v108
	v_sub_u32_e32 v60, v103, v60
	v_cvt_f32_i32_e32 v60, v60
	s_mov_b32 s4, 2.0
	s_mov_b32 s5, 0x40400000
	v_fma_f32 v60, -v96, v60, -v106
	v_cndmask_b32_e64 v68, v249, v60, s[8:9]
	v_pk_fma_f32 v[62:63], v[96:97], s[4:5], v[68:69] op_sel_hi:[1,1,0]
	s_mov_b32 s4, 0x41800000
	s_mov_b32 s5, 0x41880000
	v_fma_f32 v60, 0, v96, v68
	v_add_f32_e32 v61, v96, v68
	v_pk_fma_f32 v[66:67], v[90:91], s[90:91], v[68:69] op_sel_hi:[1,1,0]
	v_pk_fma_f32 v[64:65], v[88:89], s[4:5], v[68:69] op_sel_hi:[1,1,0]
	v_pk_fma_f32 v[78:79], v[90:91], s[92:93], v[68:69] op_sel_hi:[1,1,0]
	v_pk_fma_f32 v[76:77], v[88:89], s[34:35], v[68:69] op_sel_hi:[1,1,0]
	v_pk_fma_f32 v[110:111], v[90:91], s[22:23], v[68:69] op_sel_hi:[1,1,0]
	v_pk_fma_f32 v[108:109], v[88:89], s[72:73], v[68:69] op_sel_hi:[1,1,0]
	s_waitcnt lgkmcnt(7)
	v_mfma_f32_16x16x32_bf16 v[60:63], v[160:163], v[4:7], v[60:63]
	s_waitcnt lgkmcnt(6)
	v_mfma_f32_16x16x32_bf16 v[72:75], v[164:167], v[8:11], v[60:63]
	ds_read_b128 v[196:199], v244
	ds_read_b128 v[200:203], v244 offset:64
	s_waitcnt lgkmcnt(7)
	v_mfma_f32_16x16x32_bf16 v[60:63], v[168:171], v[4:7], v[64:67]
	s_waitcnt lgkmcnt(6)
	v_mfma_f32_16x16x32_bf16 v[68:71], v[172:175], v[8:11], v[60:63]
	ds_read_b128 v[204:207], v244 offset:2304
	ds_read_b128 v[208:211], v244 offset:2368
	s_waitcnt lgkmcnt(7)
	v_mfma_f32_16x16x32_bf16 v[60:63], v[176:179], v[4:7], v[76:79]
	s_waitcnt lgkmcnt(6)
	v_mfma_f32_16x16x32_bf16 v[60:63], v[180:183], v[8:11], v[60:63]
	ds_read_b128 v[212:215], v244 offset:4608
	ds_read_b128 v[216:219], v244 offset:4672
	s_waitcnt lgkmcnt(7)
	v_mfma_f32_16x16x32_bf16 v[64:67], v[184:187], v[4:7], v[108:111]
	s_waitcnt lgkmcnt(6)
	v_mfma_f32_16x16x32_bf16 v[64:67], v[188:191], v[8:11], v[64:67]
	ds_read_b128 v[220:223], v244 offset:6912
	ds_read_b128 v[224:227], v244 offset:6976
	v_max3_f32 v76, v72, s36, v73
	v_max3_f32 v76, v76, v74, v75
	v_max3_f32 v76, v76, v68, v69
	v_max3_f32 v76, v76, v70, v71
	v_max3_f32 v76, v76, v60, v61
	v_max3_f32 v76, v76, v62, v63
	s_nop 1
	v_max3_f32 v76, v76, v64, v65
	v_max3_f32 v76, v76, v66, v67
	v_cmp_lt_f32_e32 vcc, 0, v76
	s_cbranch_vccz .LBB0_995
	ds_bpermute_b32 v77, v115, v76
	v_max_f32_e32 v76, v76, v76
	s_waitcnt lgkmcnt(0)
	v_max_f32_e32 v77, v77, v77
	v_max_f32_e32 v76, v76, v77
	ds_bpermute_b32 v77, v114, v76
	s_waitcnt lgkmcnt(0)
	v_max3_f32 v77, 0, v76, v77
	v_sub_f32_e32 v76, 0, v77
	v_exp_f32_e32 v76, v76
	v_add_f32_e32 v106, v106, v77
	v_mul_f32_e32 v107, v107, v76
	v_pk_mul_f32 v[42:43], v[42:43], v[76:77] op_sel_hi:[1,0]
	v_pk_mul_f32 v[40:41], v[40:41], v[76:77] op_sel_hi:[1,0]
	v_pk_mul_f32 v[38:39], v[38:39], v[76:77] op_sel_hi:[1,0]
	v_pk_mul_f32 v[36:37], v[36:37], v[76:77] op_sel_hi:[1,0]
	v_pk_mul_f32 v[34:35], v[34:35], v[76:77] op_sel_hi:[1,0]
	v_pk_mul_f32 v[32:33], v[32:33], v[76:77] op_sel_hi:[1,0]
	v_pk_mul_f32 v[30:31], v[30:31], v[76:77] op_sel_hi:[1,0]
	v_pk_mul_f32 v[28:29], v[28:29], v[76:77] op_sel_hi:[1,0]
	v_sub_f32_e32 v72, v72, v77
	v_sub_f32_e32 v73, v73, v77
	v_sub_f32_e32 v74, v74, v77
	v_sub_f32_e32 v75, v75, v77
	v_sub_f32_e32 v68, v68, v77
	v_sub_f32_e32 v69, v69, v77
	v_sub_f32_e32 v70, v70, v77
	v_sub_f32_e32 v71, v71, v77
	v_sub_f32_e32 v60, v60, v77
	v_sub_f32_e32 v61, v61, v77
	v_sub_f32_e32 v62, v62, v77
	v_sub_f32_e32 v63, v63, v77
	v_sub_f32_e32 v64, v64, v77
	v_sub_f32_e32 v65, v65, v77
	v_sub_f32_e32 v66, v66, v77
	v_sub_f32_e32 v67, v67, v77
